# widened producer stores + live partial-merge gate loads hoisted behind the K-loop prologue
# baseline (speedup 1.0000x reference)
;     DEVINL bf16_t* Z() const { return (bf16_t*)(ws + OFF_Z); }
; #define TID (opq_v((int)threadIdx.x))
; template <int NI>
; DEVINL void gemm_kloop(const bf16_t* __restrict__ A, int lda, const bf16_t* __restrict__ Bt, int ldb, int K, int m0, int n0,
;                        unsigned char* lds, f32x16 (&acc)[NI][2]) {
;     const int tid = TID, lane = tid & 63, w = tid >> 6, wm = w & 3, wn = w >> 2, r = lane & 31, h = lane >> 5;
;     const int lrow = tid >> 3, cg = (tid & 7) ^ ((tid >> 4) & 7);
;     const bf16_t* ga = A + (size_t)(m0 + lrow) * lda + cg * 8;
;     const bf16_t* gb = Bt + (size_t)(n0 + lrow) * ldb + cg * 8;
;     unsigned char* da = lds + tid * 16;
;     unsigned char* db = lds + A_ST + tid * 16;
;     ...
;     const int nt = K >> 6;
;     asm volatile("s_waitcnt lgkmcnt(0)" ::: "memory");
;     __builtin_amdgcn_s_barrier();
;     GEMM_ISSUE(0, 0);
;     if (nt > 1) GEMM_ISSUE(1, 1);
;     const int sw = (r >> 1) & 7;
;     int o4[4];
; #pragma unroll
;     for (int ks = 0; ks < 4; ++ks) o4[ks] = ((ks * 2 + h) ^ sw) * 16;
; template <int NI, int MODE>
; DEVINL void merge_tile(const Ctx& c, unsigned char* lds, int m0, int n0) {
;     ...
;         for (int mi = 0; mi < 2; ++mi) {
;             const bf16_t* gp = c.Z() + (size_t)(mbase + mi * 32 + r) * ZW + Z_GZ + br * DM + nbase;
; #pragma unroll
;             for (int ni = 0; ni < NI; ++ni)
; #pragma unroll
;                 for (int g = 0; g < 4; ++g) {
;                     const u32x2 gg = *(const u32x2*)(gp + ni * 32 + 8 * g + 4 * h);
.LBB0_290:
	s_cmp_lg_u32 s6, 2
	v_mov_b32_e32 v6, v160
	s_cselect_b32 s66, s6, 3
	s_mul_i32 s8, s66, 0x1100000
	v_ashrrev_i32_e32 v2, 3, v6
	v_lshrrev_b32_e32 v0, 4, v6
	v_xor_b32_e32 v3, v0, v6
	v_add_u32_e32 v0, s4, v2
	s_mul_hi_u32 s7, s66, 0x1100000
	s_add_u32 s8, s86, s8
	v_ashrrev_i32_e32 v1, 31, v0
	s_addc_u32 s9, s87, s7
	v_lshlrev_b64 v[0:1], 10, v[0:1]
	v_lshlrev_b32_e32 v3, 4, v3
	v_lshl_add_u64 v[0:1], s[8:9], 0, v[0:1]
	v_and_b32_e32 v64, 0x70, v3
	s_lshl_b64 s[10:11], s[66:67], 20
	v_lshl_add_u64 v[150:151], v[0:1], 0, v[64:65]
	v_add_u32_e32 v0, s5, v2
	s_add_u32 s10, s43, s10
	v_ashrrev_i32_e32 v1, 31, v0
	s_addc_u32 s11, s29, s11
	v_lshlrev_b64 v[0:1], 10, v[0:1]
	v_lshl_add_u64 v[2:3], s[10:11], 0, v[0:1]
	v_lshl_add_u32 v0, v6, 4, 0
	v_add_u32_e32 v7, 0x2000, v0
	v_readfirstlane_b32 s18, v0
	s_mov_b32 m0, s18
	v_readfirstlane_b32 s17, v7
	v_add_u32_e32 v7, 0x4000, v0
	s_waitcnt lgkmcnt(0)
	s_barrier
	global_load_lds_dwordx4 v[150:151], off
	v_lshl_add_u64 v[4:5], v[150:151], 0, s[74:75]
	s_mov_b32 m0, s17
	v_readfirstlane_b32 s16, v7
	v_add_u32_e32 v7, 0x6000, v0
	v_add_u32_e32 v1, 0x8000, v0
	global_load_lds_dwordx4 v[4:5], off
	v_lshl_add_u64 v[4:5], v[150:151], 0, s[60:61]
	s_mov_b32 m0, s16
	v_readfirstlane_b32 s15, v7
	global_load_lds_dwordx4 v[4:5], off
	v_lshl_add_u64 v[4:5], v[150:151], 0, s[34:35]
	s_mov_b32 m0, s15
	v_readfirstlane_b32 s14, v1
	v_add_u32_e32 v1, 0xa000, v0
	global_load_lds_dwordx4 v[4:5], off
	v_lshl_add_u64 v[152:153], v[2:3], 0, v[64:65]
	s_mov_b32 m0, s14
	v_readfirstlane_b32 s13, v1
	v_add_u32_e32 v1, 0xc000, v0
	global_load_lds_dwordx4 v[152:153], off
	v_lshl_add_u64 v[2:3], v[152:153], 0, s[74:75]
	s_mov_b32 m0, s13
	v_readfirstlane_b32 s12, v1
	v_add_u32_e32 v1, 0xe000, v0
	global_load_lds_dwordx4 v[2:3], off
	v_lshl_add_u64 v[2:3], v[150:151], 0, s[92:93]
	s_mov_b32 m0, s12
	v_readfirstlane_b32 s11, v1
	v_add_u32_e32 v1, 0x10000, v0
	global_load_lds_dwordx4 v[2:3], off
	v_lshl_add_u64 v[2:3], v[150:151], 0, s[76:77]
	s_mov_b32 m0, s11
	v_readfirstlane_b32 s10, v1
	v_add_u32_e32 v1, 0x12000, v0
	global_load_lds_dwordx4 v[2:3], off
	v_lshl_add_u64 v[2:3], v[150:151], 0, s[48:49]
	s_mov_b32 m0, s10
	v_readfirstlane_b32 s9, v1
	v_add_u32_e32 v1, 0x14000, v0
	global_load_lds_dwordx4 v[2:3], off
	v_lshl_add_u64 v[2:3], v[150:151], 0, s[36:37]
	s_mov_b32 m0, s9
	v_readfirstlane_b32 s8, v1
	v_add_u32_e32 v1, 0x16000, v0
	global_load_lds_dwordx4 v[2:3], off
	v_lshl_add_u64 v[2:3], v[152:153], 0, s[92:93]
	s_mov_b32 m0, s8
	v_readfirstlane_b32 s7, v1
	global_load_lds_dwordx4 v[2:3], off
	v_lshl_add_u64 v[2:3], v[152:153], 0, s[76:77]
	s_mov_b32 m0, s7
	v_lshrrev_b32_e32 v1, 5, v6
	global_load_lds_dwordx4 v[2:3], off
	v_bfe_u32 v2, v6, 5, 1
	v_bfe_u32 v3, v6, 1, 3
	v_bitop3_b32 v4, v2, v3, 6 bitop3:0x36
	v_bitop3_b32 v1, v1, v3, 1 bitop3:0x6c
	v_lshlrev_b32_e32 v172, 4, v4
	v_bitop3_b32 v4, v2, v3, 4 bitop3:0x36
	v_bitop3_b32 v2, v2, v3, 2 bitop3:0x36
	v_lshlrev_b32_e32 v175, 4, v1
	v_lshlrev_b32_e32 v1, 7, v6
	v_lshlrev_b32_e32 v174, 4, v2
	v_and_b32_e32 v2, 0xf80, v1
	v_and_b32_e32 v177, 0x6f80, v1
	v_lshlrev_b32_e32 v1, 5, v6
	v_and_or_b32 v176, v1, s28, v2
	v_add_u32_e32 v1, 0x18000, v0
	v_lshl_add_u64 v[2:3], v[150:151], 0, s[84:85]
	v_readfirstlane_b32 s20, v1
	v_add_u32_e32 v1, 0x1a000, v0
	s_mov_b32 m0, s20
	v_readfirstlane_b32 s19, v1
	v_add_u32_e32 v1, 0x1c000, v0
	s_lshl_b32 s100, s66, 11
	s_mov_b32 s101, 0
	v_lshl_add_u64 v[254:255], v[146:147], 0, s[100:101]
	v_lshl_add_u64 v[242:243], v[148:149], 0, s[100:101]
	global_load_dwordx2 v[208:209], v[254:255], off
	global_load_dwordx2 v[210:211], v[254:255], off offset:16
	global_load_dwordx2 v[212:213], v[254:255], off offset:32
	global_load_dwordx2 v[214:215], v[254:255], off offset:48
	global_load_dwordx2 v[216:217], v[254:255], off offset:64
	global_load_dwordx2 v[218:219], v[254:255], off offset:80
	global_load_dwordx2 v[228:229], v[254:255], off offset:96
	global_load_dwordx2 v[254:255], v[254:255], off offset:112
	global_load_dwordx2 v[230:231], v[242:243], off
	global_load_dwordx2 v[232:233], v[242:243], off offset:16
	global_load_dwordx2 v[234:235], v[242:243], off offset:32
	global_load_dwordx2 v[236:237], v[242:243], off offset:48
	global_load_dwordx2 v[248:249], v[242:243], off offset:64
	global_load_dwordx2 v[250:251], v[242:243], off offset:80
	global_load_dwordx2 v[252:253], v[242:243], off offset:96
	global_load_dwordx2 v[242:243], v[242:243], off offset:112
	s_waitcnt vmcnt(22)
	s_barrier
; #define MFMA32(a, b, c) __builtin_amdgcn_mfma_f32_32x32x16_bf16((a), (b), (c), 0, 0, 0)
; template <int NI>
; DEVINL void gemm_kloop(const bf16_t* __restrict__ A, int lda, const bf16_t* __restrict__ Bt, int ldb, int K, int m0, int n0,
;                        unsigned char* lds, f32x16 (&acc)[NI][2]) {
;     ...
;     auto compute = [&](int st_) {
;         const unsigned char* pa = lds + st_ * STAGE + (wm * 64 + r) * 128;
;         const unsigned char* pb = lds + st_ * STAGE + A_ST + (wn * 32 * NI + r) * 128;
;         bf16x8 af[2][2], bfr[2][NI];
; #pragma unroll
;         for (int i = 0; i < 2; ++i) af[0][i] = *(const bf16x8*)(pa + i * 32 * 128 + o4[0]);
; #pragma unroll
;         for (int i = 0; i < NI; ++i) bfr[0][i] = *(const bf16x8*)(pb + i * 32 * 128 + o4[0]);
; #pragma unroll
;         for (int ks = 0; ks < 4; ++ks) {
;             if (ks < 3) {
; #pragma unroll
;                 for (int i = 0; i < 2; ++i) af[(ks + 1) & 1][i] = *(const bf16x8*)(pa + i * 32 * 128 + o4[ks + 1]);
; #pragma unroll
;                 for (int i = 0; i < NI; ++i) bfr[(ks + 1) & 1][i] = *(const bf16x8*)(pb + i * 32 * 128 + o4[ks + 1]);
;             }
; #pragma unroll
;             for (int ni = 0; ni < NI; ++ni)
; #pragma unroll
;                 for (int mi = 0; mi < 2; ++mi) acc[ni][mi] = MFMA32(bfr[ks & 1][ni], af[ks & 1][mi], acc[ni][mi]);
;         }
;     };
;     int t = 0;
;     for (; t + 2 < nt; ++t) {
;         if (NI == 2) asm volatile("s_waitcnt vmcnt(6)" ::: "memory"); else asm volatile("s_waitcnt vmcnt(5)" ::: "memory");
;         __builtin_amdgcn_s_barrier();
;         { const int s2 = (cur >= 1) ? cur - 1 : 2; GEMM_ISSUE(s2, t + 2); }
;         compute(cur);
;         cur = (cur == 2) ? 0 : cur + 1;
;     }
	global_load_lds_dwordx4 v[2:3], off
	v_lshl_add_u64 v[2:3], v[150:151], 0, s[78:79]
	s_mov_b32 m0, s19
	v_readfirstlane_b32 s21, v1
	v_add_u32_e32 v1, 0x1e000, v0
	global_load_lds_dwordx4 v[2:3], off
	v_lshl_add_u64 v[2:3], v[150:151], 0, s[30:31]
	s_mov_b32 m0, s21
	v_readfirstlane_b32 s24, v1
	v_add_u32_e32 v1, 0x20000, v0
	global_load_lds_dwordx4 v[2:3], off
	v_lshl_add_u64 v[2:3], v[150:151], 0, s[50:51]
	s_mov_b32 m0, s24
	v_readfirstlane_b32 s25, v1
	v_add_u32_e32 v0, 0x22000, v0
	global_load_lds_dwordx4 v[2:3], off
	v_lshl_add_u64 v[2:3], v[152:153], 0, s[84:85]
	s_mov_b32 m0, s25
	v_readfirstlane_b32 s26, v0
	global_load_lds_dwordx4 v[2:3], off
	v_lshl_add_u64 v[2:3], v[152:153], 0, s[78:79]
	s_mov_b32 m0, s26
	v_add_u32_e32 v156, 0, v177
	v_add_u32_e32 v159, 0, v176
	global_load_lds_dwordx4 v[2:3], off
	v_add_u32_e32 v64, v156, v175
	v_add_u32_e32 v143, v159, v175
	v_lshlrev_b32_e32 v173, 4, v4
	ds_read_b128 v[4:7], v64
	ds_read_b128 v[0:3], v64 offset:4096
	ds_read_b128 v[8:11], v143 offset:32768
	ds_read_b128 v[12:15], v143 offset:36864
	s_waitcnt lgkmcnt(0)
	v_mfma_f32_32x32x16_bf16 v[48:63], v[8:11], v[4:7], 0
	v_add_u32_e32 v154, v156, v174
	v_add_u32_e32 v157, v159, v174
	ds_read_b128 v[130:133], v154
	ds_read_b128 v[134:137], v154 offset:4096
	ds_read_b128 v[168:171], v157 offset:32768
	ds_read_b128 v[178:181], v157 offset:36864
	v_add_u32_e32 v155, v156, v173
	v_add_u32_e32 v158, v159, v173
	ds_read_b128 v[182:185], v155
	ds_read_b128 v[186:189], v155 offset:4096
	v_mfma_f32_32x32x16_bf16 v[32:47], v[12:15], v[4:7], 0
	ds_read_b128 v[190:193], v158 offset:32768
	ds_read_b128 v[194:197], v158 offset:36864
	v_add_u32_e32 v156, v156, v172
	v_add_u32_e32 v159, v159, v172
	s_mov_b32 m0, s18
	s_add_i32 s27, 0, 0x14000
	v_add_u32_e32 v207, s42, v176
	s_lshl_b32 s66, s66, 11
	v_mfma_f32_32x32x16_bf16 v[16:31], v[8:11], v[0:3], 0
	s_add_i32 s6, s6, 1
	v_mfma_f32_32x32x16_bf16 v[0:15], v[12:15], v[0:3], 0
	s_waitcnt lgkmcnt(0)
	v_mfma_f32_32x32x16_bf16 v[48:63], v[168:171], v[130:133], v[48:63]
	v_mfma_f32_32x32x16_bf16 v[32:47], v[178:181], v[130:133], v[32:47]
	v_mfma_f32_32x32x16_bf16 v[16:31], v[168:171], v[134:137], v[16:31]
	v_mfma_f32_32x32x16_bf16 v[0:15], v[178:181], v[134:137], v[0:15]
	ds_read_b128 v[130:133], v156
	ds_read_b128 v[134:137], v156 offset:4096
	ds_read_b128 v[168:171], v159 offset:32768
	ds_read_b128 v[178:181], v159 offset:36864
	s_waitcnt vmcnt(22)
	s_barrier
	v_mfma_f32_32x32x16_bf16 v[48:63], v[190:193], v[182:185], v[48:63]
	v_mfma_f32_32x32x16_bf16 v[32:47], v[194:197], v[182:185], v[32:47]
	v_mfma_f32_32x32x16_bf16 v[16:31], v[190:193], v[186:189], v[16:31]
	v_mfma_f32_32x32x16_bf16 v[0:15], v[194:197], v[186:189], v[0:15]
	s_waitcnt lgkmcnt(0)
	v_mfma_f32_32x32x16_bf16 v[48:63], v[168:171], v[130:133], v[48:63]
	v_mfma_f32_32x32x16_bf16 v[32:47], v[178:181], v[130:133], v[32:47]
	v_lshl_add_u64 v[130:131], v[150:151], 0, s[88:89]
	global_load_lds_dwordx4 v[130:131], off
	v_lshl_add_u64 v[130:131], v[150:151], 0, s[80:81]
	s_mov_b32 m0, s17
	s_nop 0
	global_load_lds_dwordx4 v[130:131], off
	v_lshl_add_u64 v[130:131], v[150:151], 0, s[96:97]
	s_mov_b32 m0, s16
	v_mfma_f32_32x32x16_bf16 v[16:31], v[168:171], v[134:137], v[16:31]
	global_load_lds_dwordx4 v[130:131], off
	v_lshl_add_u64 v[130:131], v[150:151], 0, s[52:53]
	s_mov_b32 m0, s15
	v_add_u32_e32 v171, s27, v176
	global_load_lds_dwordx4 v[130:131], off
	v_lshl_add_u64 v[130:131], v[152:153], 0, s[88:89]
	s_mov_b32 m0, s14
	v_mfma_f32_32x32x16_bf16 v[0:15], v[178:181], v[134:137], v[0:15]
	global_load_lds_dwordx4 v[130:131], off
	v_lshl_add_u64 v[130:131], v[152:153], 0, s[80:81]
	s_mov_b32 m0, s13
	v_add_u32_e32 v168, v171, v175
	global_load_lds_dwordx4 v[130:131], off
	ds_read_b128 v[134:137], v64 offset:49152
	ds_read_b128 v[130:133], v64 offset:53248
	ds_read_b128 v[178:181], v168
	ds_read_b128 v[182:185], v168 offset:4096
	ds_read_b128 v[186:189], v154 offset:49152
	ds_read_b128 v[190:193], v154 offset:53248
	s_waitcnt lgkmcnt(0)
	v_mfma_f32_32x32x16_bf16 v[48:63], v[178:181], v[134:137], v[48:63]
	v_add_u32_e32 v169, v171, v174
	ds_read_b128 v[194:197], v169
	ds_read_b128 v[198:201], v169 offset:4096
	v_add_u32_e32 v170, v171, v173
	v_add_u32_e32 v171, v171, v172
	s_mov_b32 m0, s12
	s_add_i32 s27, 0, 0x18000
	v_add_u32_e32 v206, s27, v177
	v_mfma_f32_32x32x16_bf16 v[32:47], v[182:185], v[134:137], v[32:47]
	v_add_u32_e32 v177, v206, v175
	v_add_u32_e32 v175, v207, v175
	v_add_u32_e32 v176, v206, v174
	v_add_u32_e32 v174, v207, v174
	s_cmp_lg_u32 s6, 3
	v_mfma_f32_32x32x16_bf16 v[16:31], v[178:181], v[130:133], v[16:31]
	v_mfma_f32_32x32x16_bf16 v[0:15], v[182:185], v[130:133], v[0:15]
	ds_read_b128 v[130:133], v155 offset:49152
	ds_read_b128 v[134:137], v155 offset:53248
	ds_read_b128 v[178:181], v170
	ds_read_b128 v[182:185], v170 offset:4096
	s_waitcnt lgkmcnt(0)
	v_mfma_f32_32x32x16_bf16 v[48:63], v[194:197], v[186:189], v[48:63]
	v_mfma_f32_32x32x16_bf16 v[32:47], v[198:201], v[186:189], v[32:47]
	v_mfma_f32_32x32x16_bf16 v[16:31], v[194:197], v[190:193], v[16:31]
	v_mfma_f32_32x32x16_bf16 v[0:15], v[198:201], v[190:193], v[0:15]
	ds_read_b128 v[186:189], v156 offset:49152
	ds_read_b128 v[190:193], v156 offset:53248
	ds_read_b128 v[194:197], v171
	ds_read_b128 v[198:201], v171 offset:4096
	s_waitcnt vmcnt(6)
	s_barrier
; #define MFMA32(a, b, c) __builtin_amdgcn_mfma_f32_32x32x16_bf16((a), (b), (c), 0, 0, 0)
; template <int NI>
; DEVINL void gemm_kloop(const bf16_t* __restrict__ A, int lda, const bf16_t* __restrict__ Bt, int ldb, int K, int m0, int n0,
;                        unsigned char* lds, f32x16 (&acc)[NI][2]) {
;     ...
;     auto compute = [&](int st_) {
;         const unsigned char* pa = lds + st_ * STAGE + (wm * 64 + r) * 128;
;         const unsigned char* pb = lds + st_ * STAGE + A_ST + (wn * 32 * NI + r) * 128;
;         bf16x8 af[2][2], bfr[2][NI];
; #pragma unroll
;         for (int i = 0; i < 2; ++i) af[0][i] = *(const bf16x8*)(pa + i * 32 * 128 + o4[0]);
; #pragma unroll
;         for (int i = 0; i < NI; ++i) bfr[0][i] = *(const bf16x8*)(pb + i * 32 * 128 + o4[0]);
; #pragma unroll
;         for (int ks = 0; ks < 4; ++ks) {
;             if (ks < 3) {
; #pragma unroll
;                 for (int i = 0; i < 2; ++i) af[(ks + 1) & 1][i] = *(const bf16x8*)(pa + i * 32 * 128 + o4[ks + 1]);
; #pragma unroll
;                 for (int i = 0; i < NI; ++i) bfr[(ks + 1) & 1][i] = *(const bf16x8*)(pb + i * 32 * 128 + o4[ks + 1]);
;             }
; #pragma unroll
;             for (int ni = 0; ni < NI; ++ni)
; #pragma unroll
;                 for (int mi = 0; mi < 2; ++mi) acc[ni][mi] = MFMA32(bfr[ks & 1][ni], af[ks & 1][mi], acc[ni][mi]);
;         }
;     };
;     int t = 0;
;     for (; t + 2 < nt; ++t) {
;         if (NI == 2) asm volatile("s_waitcnt vmcnt(6)" ::: "memory"); else asm volatile("s_waitcnt vmcnt(5)" ::: "memory");
;         __builtin_amdgcn_s_barrier();
;         { const int s2 = (cur >= 1) ? cur - 1 : 2; GEMM_ISSUE(s2, t + 2); }
;         compute(cur);
;         cur = (cur == 2) ? 0 : cur + 1;
;     }
	v_mfma_f32_32x32x16_bf16 v[48:63], v[178:181], v[130:133], v[48:63]
	v_mfma_f32_32x32x16_bf16 v[32:47], v[182:185], v[130:133], v[32:47]
	v_lshl_add_u64 v[130:131], v[150:151], 0, s[58:59]
	global_load_lds_dwordx4 v[130:131], off
	v_lshl_add_u64 v[130:131], v[150:151], 0, s[82:83]
	s_mov_b32 m0, s11
	s_nop 0
	global_load_lds_dwordx4 v[130:131], off
	v_lshl_add_u64 v[130:131], v[150:151], 0, s[62:63]
	s_mov_b32 m0, s10
	v_mfma_f32_32x32x16_bf16 v[16:31], v[178:181], v[134:137], v[16:31]
	global_load_lds_dwordx4 v[130:131], off
	v_lshl_add_u64 v[130:131], v[150:151], 0, s[54:55]
	s_mov_b32 m0, s9
	s_nop 0
	global_load_lds_dwordx4 v[130:131], off
	v_mfma_f32_32x32x16_bf16 v[0:15], v[182:185], v[134:137], v[0:15]
	v_lshl_add_u64 v[130:131], v[152:153], 0, s[58:59]
	s_mov_b32 m0, s8
	s_nop 0
	global_load_lds_dwordx4 v[130:131], off
	v_lshl_add_u64 v[130:131], v[152:153], 0, s[82:83]
	s_mov_b32 m0, s7
	s_waitcnt lgkmcnt(0)
	v_mfma_f32_32x32x16_bf16 v[48:63], v[194:197], v[186:189], v[48:63]
	global_load_lds_dwordx4 v[130:131], off
	ds_read_b128 v[134:137], v177
	ds_read_b128 v[130:133], v177 offset:4096
	ds_read_b128 v[178:181], v175
	ds_read_b128 v[182:185], v175 offset:4096
	s_mov_b32 m0, s20
	v_mfma_f32_32x32x16_bf16 v[32:47], v[198:201], v[186:189], v[32:47]
	v_mfma_f32_32x32x16_bf16 v[16:31], v[194:197], v[190:193], v[16:31]
	v_mfma_f32_32x32x16_bf16 v[0:15], v[198:201], v[190:193], v[0:15]
	ds_read_b128 v[186:189], v176
	ds_read_b128 v[190:193], v176 offset:4096
	ds_read_b128 v[194:197], v174
	ds_read_b128 v[198:201], v174 offset:4096
	s_waitcnt lgkmcnt(0)
	v_mfma_f32_32x32x16_bf16 v[48:63], v[178:181], v[134:137], v[48:63]
	v_mfma_f32_32x32x16_bf16 v[32:47], v[182:185], v[134:137], v[32:47]
	v_mfma_f32_32x32x16_bf16 v[16:31], v[178:181], v[130:133], v[16:31]
	v_mfma_f32_32x32x16_bf16 v[0:15], v[182:185], v[130:133], v[0:15]
	v_add_u32_e32 v130, v206, v173
	v_add_u32_e32 v131, v207, v173
	ds_read_b128 v[134:137], v130
	ds_read_b128 v[178:181], v130 offset:4096
	ds_read_b128 v[182:185], v131
	ds_read_b128 v[202:205], v131 offset:4096
	v_add_u32_e32 v132, v206, v172
	v_add_u32_e32 v133, v207, v172
	v_mfma_f32_32x32x16_bf16 v[48:63], v[194:197], v[186:189], v[48:63]
	v_mfma_f32_32x32x16_bf16 v[32:47], v[198:201], v[186:189], v[32:47]
	v_mfma_f32_32x32x16_bf16 v[16:31], v[194:197], v[190:193], v[16:31]
	v_mfma_f32_32x32x16_bf16 v[0:15], v[198:201], v[190:193], v[0:15]
	ds_read_b128 v[186:189], v132
	ds_read_b128 v[190:193], v132 offset:4096
	ds_read_b128 v[194:197], v133
	ds_read_b128 v[198:201], v133 offset:4096
	s_waitcnt vmcnt(6)
	s_barrier
	s_waitcnt lgkmcnt(0)
	v_mfma_f32_32x32x16_bf16 v[48:63], v[182:185], v[134:137], v[48:63]
	v_mfma_f32_32x32x16_bf16 v[32:47], v[202:205], v[134:137], v[32:47]
	v_lshl_add_u64 v[134:135], v[150:151], 0, s[64:65]
	global_load_lds_dwordx4 v[134:135], off
	v_lshl_add_u64 v[134:135], v[150:151], 0, s[68:69]
	s_mov_b32 m0, s19
	s_nop 0
	global_load_lds_dwordx4 v[134:135], off
	v_mfma_f32_32x32x16_bf16 v[16:31], v[182:185], v[178:181], v[16:31]
	v_lshl_add_u64 v[134:135], v[150:151], 0, s[90:91]
	s_mov_b32 m0, s21
	s_nop 0
	global_load_lds_dwordx4 v[134:135], off
	v_lshl_add_u64 v[134:135], v[150:151], 0, s[94:95]
	s_mov_b32 m0, s24
	v_mfma_f32_32x32x16_bf16 v[0:15], v[202:205], v[178:181], v[0:15]
	global_load_lds_dwordx4 v[134:135], off
	v_lshl_add_u64 v[134:135], v[152:153], 0, s[64:65]
	s_mov_b32 m0, s25
	s_nop 0
	global_load_lds_dwordx4 v[134:135], off
	v_mfma_f32_32x32x16_bf16 v[48:63], v[194:197], v[186:189], v[48:63]
	v_lshl_add_u64 v[134:135], v[152:153], 0, s[68:69]
	s_mov_b32 m0, s26
	s_nop 0
	global_load_lds_dwordx4 v[134:135], off
	s_mov_b32 m0, s18
	v_mfma_f32_32x32x16_bf16 v[32:47], v[198:201], v[186:189], v[32:47]
	v_mfma_f32_32x32x16_bf16 v[16:31], v[194:197], v[190:193], v[16:31]
	v_mfma_f32_32x32x16_bf16 v[0:15], v[198:201], v[190:193], v[0:15]
	ds_read_b128 v[134:137], v64
	ds_read_b128 v[178:181], v64 offset:4096
	ds_read_b128 v[182:185], v143 offset:32768
	ds_read_b128 v[186:189], v143 offset:36864
	ds_read_b128 v[190:193], v154
	ds_read_b128 v[194:197], v154 offset:4096
	ds_read_b128 v[198:201], v157 offset:32768
	ds_read_b128 v[202:205], v157 offset:36864
	s_waitcnt lgkmcnt(0)
	v_mfma_f32_32x32x16_bf16 v[48:63], v[182:185], v[134:137], v[48:63]
	v_mfma_f32_32x32x16_bf16 v[32:47], v[186:189], v[134:137], v[32:47]
	v_mfma_f32_32x32x16_bf16 v[16:31], v[182:185], v[178:181], v[16:31]
	v_mfma_f32_32x32x16_bf16 v[0:15], v[186:189], v[178:181], v[0:15]
	ds_read_b128 v[134:137], v155
	ds_read_b128 v[178:181], v155 offset:4096
	ds_read_b128 v[182:185], v158 offset:32768
	ds_read_b128 v[186:189], v158 offset:36864
	v_mfma_f32_32x32x16_bf16 v[48:63], v[198:201], v[190:193], v[48:63]
	v_mfma_f32_32x32x16_bf16 v[32:47], v[202:205], v[190:193], v[32:47]
	v_mfma_f32_32x32x16_bf16 v[16:31], v[198:201], v[194:197], v[16:31]
	v_mfma_f32_32x32x16_bf16 v[0:15], v[202:205], v[194:197], v[0:15]
	ds_read_b128 v[190:193], v156
	ds_read_b128 v[194:197], v156 offset:4096
	ds_read_b128 v[198:201], v159 offset:32768
	ds_read_b128 v[202:205], v159 offset:36864
	s_waitcnt vmcnt(6)
	s_barrier
; #define MFMA32(a, b, c) __builtin_amdgcn_mfma_f32_32x32x16_bf16((a), (b), (c), 0, 0, 0)
; template <int NI>
; DEVINL void gemm_kloop(const bf16_t* __restrict__ A, int lda, const bf16_t* __restrict__ Bt, int ldb, int K, int m0, int n0,
;                        unsigned char* lds, f32x16 (&acc)[NI][2]) {
;     ...
;     auto compute = [&](int st_) {
;         const unsigned char* pa = lds + st_ * STAGE + (wm * 64 + r) * 128;
;         const unsigned char* pb = lds + st_ * STAGE + A_ST + (wn * 32 * NI + r) * 128;
;         bf16x8 af[2][2], bfr[2][NI];
; #pragma unroll
;         for (int i = 0; i < 2; ++i) af[0][i] = *(const bf16x8*)(pa + i * 32 * 128 + o4[0]);
; #pragma unroll
;         for (int i = 0; i < NI; ++i) bfr[0][i] = *(const bf16x8*)(pb + i * 32 * 128 + o4[0]);
; #pragma unroll
;         for (int ks = 0; ks < 4; ++ks) {
;             if (ks < 3) {
; #pragma unroll
;                 for (int i = 0; i < 2; ++i) af[(ks + 1) & 1][i] = *(const bf16x8*)(pa + i * 32 * 128 + o4[ks + 1]);
; #pragma unroll
;                 for (int i = 0; i < NI; ++i) bfr[(ks + 1) & 1][i] = *(const bf16x8*)(pb + i * 32 * 128 + o4[ks + 1]);
;             }
; #pragma unroll
;             for (int ni = 0; ni < NI; ++ni)
; #pragma unroll
;                 for (int mi = 0; mi < 2; ++mi) acc[ni][mi] = MFMA32(bfr[ks & 1][ni], af[ks & 1][mi], acc[ni][mi]);
;         }
;     };
;     int t = 0;
;     for (; t + 2 < nt; ++t) {
;         if (NI == 2) asm volatile("s_waitcnt vmcnt(6)" ::: "memory"); else asm volatile("s_waitcnt vmcnt(5)" ::: "memory");
;         __builtin_amdgcn_s_barrier();
;         { const int s2 = (cur >= 1) ? cur - 1 : 2; GEMM_ISSUE(s2, t + 2); }
;         compute(cur);
;         cur = (cur == 2) ? 0 : cur + 1;
;     }
	s_waitcnt lgkmcnt(0)
	v_mfma_f32_32x32x16_bf16 v[48:63], v[182:185], v[134:137], v[48:63]
	v_mfma_f32_32x32x16_bf16 v[32:47], v[186:189], v[134:137], v[32:47]
	v_lshl_add_u64 v[134:135], v[150:151], 0, s[2:3]
	global_load_lds_dwordx4 v[134:135], off
	v_lshl_add_u64 v[134:135], v[150:151], 0, s[70:71]
	s_mov_b32 m0, s17
	s_nop 0
	global_load_lds_dwordx4 v[134:135], off
	v_mfma_f32_32x32x16_bf16 v[16:31], v[182:185], v[178:181], v[16:31]
	v_lshl_add_u64 v[134:135], v[150:151], 0, s[72:73]
	s_mov_b32 m0, s16
	s_nop 0
	global_load_lds_dwordx4 v[134:135], off
	v_lshl_add_u64 v[134:135], v[150:151], 0, vcc
	s_mov_b32 m0, s15
	v_mfma_f32_32x32x16_bf16 v[0:15], v[186:189], v[178:181], v[0:15]
	global_load_lds_dwordx4 v[134:135], off
	v_lshl_add_u64 v[134:135], v[152:153], 0, s[2:3]
	s_mov_b32 m0, s14
	s_nop 0
	global_load_lds_dwordx4 v[134:135], off
	v_mfma_f32_32x32x16_bf16 v[48:63], v[198:201], v[190:193], v[48:63]
	v_lshl_add_u64 v[134:135], v[152:153], 0, s[70:71]
	s_mov_b32 m0, s13
	s_nop 0
	global_load_lds_dwordx4 v[134:135], off
	s_mov_b32 m0, s12
	v_mfma_f32_32x32x16_bf16 v[32:47], v[202:205], v[190:193], v[32:47]
	v_mfma_f32_32x32x16_bf16 v[16:31], v[198:201], v[194:197], v[16:31]
	v_mfma_f32_32x32x16_bf16 v[0:15], v[202:205], v[194:197], v[0:15]
	ds_read_b128 v[134:137], v64 offset:49152
	ds_read_b128 v[178:181], v64 offset:53248
	ds_read_b128 v[182:185], v168
	ds_read_b128 v[186:189], v168 offset:4096
	ds_read_b128 v[190:193], v154 offset:49152
	ds_read_b128 v[194:197], v154 offset:53248
	ds_read_b128 v[198:201], v169
	ds_read_b128 v[202:205], v169 offset:4096
	s_waitcnt lgkmcnt(0)
	v_mfma_f32_32x32x16_bf16 v[48:63], v[182:185], v[134:137], v[48:63]
	v_mfma_f32_32x32x16_bf16 v[32:47], v[186:189], v[134:137], v[32:47]
	v_mfma_f32_32x32x16_bf16 v[16:31], v[182:185], v[178:181], v[16:31]
	v_mfma_f32_32x32x16_bf16 v[0:15], v[186:189], v[178:181], v[0:15]
	ds_read_b128 v[134:137], v155 offset:49152
	ds_read_b128 v[178:181], v155 offset:53248
	ds_read_b128 v[182:185], v170
	ds_read_b128 v[186:189], v170 offset:4096
	v_mfma_f32_32x32x16_bf16 v[48:63], v[198:201], v[190:193], v[48:63]
	v_mfma_f32_32x32x16_bf16 v[32:47], v[202:205], v[190:193], v[32:47]
	v_mfma_f32_32x32x16_bf16 v[16:31], v[198:201], v[194:197], v[16:31]
	v_mfma_f32_32x32x16_bf16 v[0:15], v[202:205], v[194:197], v[0:15]
	ds_read_b128 v[190:193], v156 offset:49152
	ds_read_b128 v[194:197], v156 offset:53248
	ds_read_b128 v[198:201], v171
	ds_read_b128 v[202:205], v171 offset:4096
	s_waitcnt vmcnt(6)
	s_barrier
	s_waitcnt lgkmcnt(0)
	v_mfma_f32_32x32x16_bf16 v[48:63], v[182:185], v[134:137], v[48:63]
	v_mfma_f32_32x32x16_bf16 v[32:47], v[186:189], v[134:137], v[32:47]
	v_lshl_add_u64 v[134:135], v[150:151], 0, s[40:41]
	global_load_lds_dwordx4 v[134:135], off
	v_lshl_add_u64 v[134:135], v[150:151], 0, s[44:45]
	s_mov_b32 m0, s11
	s_nop 0
	global_load_lds_dwordx4 v[134:135], off
	v_mfma_f32_32x32x16_bf16 v[16:31], v[182:185], v[178:181], v[16:31]
	v_lshl_add_u64 v[134:135], v[150:151], 0, s[22:23]
	s_mov_b32 m0, s10
	s_nop 0
	global_load_lds_dwordx4 v[134:135], off
	v_lshl_add_u64 v[134:135], v[150:151], 0, s[56:57]
	s_mov_b32 m0, s9
	v_mfma_f32_32x32x16_bf16 v[0:15], v[186:189], v[178:181], v[0:15]
	global_load_lds_dwordx4 v[134:135], off
	v_lshl_add_u64 v[134:135], v[152:153], 0, s[40:41]
	s_mov_b32 m0, s8
	s_nop 0
	global_load_lds_dwordx4 v[134:135], off
	v_mfma_f32_32x32x16_bf16 v[48:63], v[198:201], v[190:193], v[48:63]
	v_lshl_add_u64 v[134:135], v[152:153], 0, s[44:45]
	s_mov_b32 m0, s7
	s_nop 0
	global_load_lds_dwordx4 v[134:135], off
	v_mfma_f32_32x32x16_bf16 v[32:47], v[202:205], v[190:193], v[32:47]
	v_mfma_f32_32x32x16_bf16 v[16:31], v[198:201], v[194:197], v[16:31]
	v_mfma_f32_32x32x16_bf16 v[0:15], v[202:205], v[194:197], v[0:15]
	ds_read_b128 v[134:137], v177
	ds_read_b128 v[150:153], v177 offset:4096
	ds_read_b128 v[178:181], v175
	ds_read_b128 v[182:185], v175 offset:4096
	ds_read_b128 v[186:189], v176
	ds_read_b128 v[190:193], v176 offset:4096
	ds_read_b128 v[194:197], v174
	ds_read_b128 v[172:175], v174 offset:4096
	s_waitcnt lgkmcnt(0)
	v_mfma_f32_32x32x16_bf16 v[48:63], v[178:181], v[134:137], v[48:63]
	v_mfma_f32_32x32x16_bf16 v[32:47], v[182:185], v[134:137], v[32:47]
	v_mfma_f32_32x32x16_bf16 v[16:31], v[178:181], v[150:153], v[16:31]
	v_mfma_f32_32x32x16_bf16 v[0:15], v[182:185], v[150:153], v[0:15]
	ds_read_b128 v[134:137], v130
	ds_read_b128 v[150:153], v130 offset:4096
	ds_read_b128 v[176:179], v131
	ds_read_b128 v[180:183], v131 offset:4096
	v_mfma_f32_32x32x16_bf16 v[48:63], v[194:197], v[186:189], v[48:63]
	v_mfma_f32_32x32x16_bf16 v[32:47], v[172:175], v[186:189], v[32:47]
	v_mfma_f32_32x32x16_bf16 v[16:31], v[194:197], v[190:193], v[16:31]
	v_mfma_f32_32x32x16_bf16 v[0:15], v[172:175], v[190:193], v[0:15]
	ds_read_b128 v[172:175], v132
	ds_read_b128 v[184:187], v132 offset:4096
	ds_read_b128 v[188:191], v133
	ds_read_b128 v[130:133], v133 offset:4096
	s_waitcnt vmcnt(6)
	s_barrier
;     DEVINL bf16_t* Z() const { return (bf16_t*)(ws + OFF_Z); }
; DEVINL float bflo(unsigned u) { return __uint_as_float(u << 16); }
; DEVINL float bfhi(unsigned u) { return __uint_as_float(u & 0xffff0000u); }
; template <int NI>
; DEVINL void gemm_kloop(const bf16_t* __restrict__ A, int lda, const bf16_t* __restrict__ Bt, int ldb, int K, int m0, int n0,
;                        unsigned char* lds, f32x16 (&acc)[NI][2]) {
;     ...
;     if (nt >= 2) {
;         if (NI == 2) asm volatile("s_waitcnt vmcnt(6)" ::: "memory"); else asm volatile("s_waitcnt vmcnt(5)" ::: "memory");
;         __builtin_amdgcn_s_barrier();
;         compute(cur);
;         cur = (cur == 2) ? 0 : cur + 1;
;     }
;     asm volatile("s_waitcnt vmcnt(0)" ::: "memory");
;     __builtin_amdgcn_s_barrier();
;     compute(cur);
; template <int NI, int MODE>
; DEVINL void merge_tile(const Ctx& c, unsigned char* lds, int m0, int n0) {
;     ...
;         for (int mi = 0; mi < 2; ++mi) {
;             const bf16_t* gp = c.Z() + (size_t)(mbase + mi * 32 + r) * ZW + Z_GZ + br * DM + nbase;
; #pragma unroll
;             for (int ni = 0; ni < NI; ++ni)
; #pragma unroll
;                 for (int g = 0; g < 4; ++g) {
;                     const u32x2 gg = *(const u32x2*)(gp + ni * 32 + 8 * g + 4 * h);
;                     mer[ni][mi][4 * g + 0] += bflo(gg[0]) * acc[ni][mi][4 * g + 0];
;                     mer[ni][mi][4 * g + 1] += bfhi(gg[0]) * acc[ni][mi][4 * g + 1];
;                     mer[ni][mi][4 * g + 2] += bflo(gg[1]) * acc[ni][mi][4 * g + 2];
;                     mer[ni][mi][4 * g + 3] += bfhi(gg[1]) * acc[ni][mi][4 * g + 3];
;                 }
	s_waitcnt lgkmcnt(0)
	v_mfma_f32_32x32x16_bf16 v[48:63], v[176:179], v[134:137], v[48:63]
	v_mfma_f32_32x32x16_bf16 v[32:47], v[180:183], v[134:137], v[32:47]
	v_mfma_f32_32x32x16_bf16 v[16:31], v[176:179], v[150:153], v[16:31]
	v_mfma_f32_32x32x16_bf16 v[0:15], v[180:183], v[150:153], v[0:15]
	v_mfma_f32_32x32x16_bf16 v[48:63], v[188:191], v[172:175], v[48:63]
	v_mfma_f32_32x32x16_bf16 v[32:47], v[130:133], v[172:175], v[32:47]
	v_mfma_f32_32x32x16_bf16 v[16:31], v[188:191], v[184:187], v[16:31]
	v_mfma_f32_32x32x16_bf16 v[0:15], v[130:133], v[184:187], v[0:15]
	ds_read_b128 v[130:133], v64
	ds_read_b128 v[134:137], v64 offset:4096
	ds_read_b128 v[150:153], v143 offset:32768
	ds_read_b128 v[172:175], v143 offset:36864
	ds_read_b128 v[176:179], v154
	ds_read_b128 v[180:183], v154 offset:4096
	ds_read_b128 v[184:187], v157 offset:32768
	ds_read_b128 v[188:191], v157 offset:36864
	s_waitcnt lgkmcnt(0)
	v_mfma_f32_32x32x16_bf16 v[48:63], v[150:153], v[130:133], v[48:63]
	v_mfma_f32_32x32x16_bf16 v[32:47], v[172:175], v[130:133], v[32:47]
	v_mfma_f32_32x32x16_bf16 v[16:31], v[150:153], v[134:137], v[16:31]
	v_mfma_f32_32x32x16_bf16 v[0:15], v[172:175], v[134:137], v[0:15]
	ds_read_b128 v[130:133], v155
	ds_read_b128 v[134:137], v155 offset:4096
	ds_read_b128 v[150:153], v158 offset:32768
	ds_read_b128 v[172:175], v158 offset:36864
	v_mfma_f32_32x32x16_bf16 v[48:63], v[184:187], v[176:179], v[48:63]
	v_mfma_f32_32x32x16_bf16 v[32:47], v[188:191], v[176:179], v[32:47]
	v_mfma_f32_32x32x16_bf16 v[16:31], v[184:187], v[180:183], v[16:31]
	v_mfma_f32_32x32x16_bf16 v[0:15], v[188:191], v[180:183], v[0:15]
	ds_read_b128 v[176:179], v156
	ds_read_b128 v[180:183], v156 offset:4096
	ds_read_b128 v[184:187], v159 offset:32768
	ds_read_b128 v[188:191], v159 offset:36864
	s_waitcnt vmcnt(0)
	s_barrier
	s_waitcnt lgkmcnt(0)
	v_mfma_f32_32x32x16_bf16 v[48:63], v[150:153], v[130:133], v[48:63]
	v_mfma_f32_32x32x16_bf16 v[32:47], v[172:175], v[130:133], v[32:47]
	v_mfma_f32_32x32x16_bf16 v[16:31], v[150:153], v[134:137], v[16:31]
	v_mfma_f32_32x32x16_bf16 v[0:15], v[172:175], v[134:137], v[0:15]
	v_mfma_f32_32x32x16_bf16 v[48:63], v[184:187], v[176:179], v[48:63]
	v_mfma_f32_32x32x16_bf16 v[32:47], v[188:191], v[176:179], v[32:47]
	v_mfma_f32_32x32x16_bf16 v[16:31], v[184:187], v[180:183], v[16:31]
	v_mfma_f32_32x32x16_bf16 v[0:15], v[188:191], v[180:183], v[0:15]
	ds_read_b128 v[130:133], v64 offset:49152
	ds_read_b128 v[134:137], v64 offset:53248
	ds_read_b128 v[150:153], v168
	ds_read_b128 v[172:175], v168 offset:4096
	ds_read_b128 v[176:179], v154 offset:49152
	ds_read_b128 v[180:183], v154 offset:53248
	ds_read_b128 v[184:187], v169
	ds_read_b128 v[188:191], v169 offset:4096
	s_waitcnt lgkmcnt(0)
	v_mfma_f32_32x32x16_bf16 v[48:63], v[150:153], v[130:133], v[48:63]
	v_mfma_f32_32x32x16_bf16 v[32:47], v[172:175], v[130:133], v[32:47]
	v_mfma_f32_32x32x16_bf16 v[48:63], v[184:187], v[176:179], v[48:63]
	v_mfma_f32_32x32x16_bf16 v[32:47], v[188:191], v[176:179], v[32:47]
	v_mfma_f32_32x32x16_bf16 v[16:31], v[150:153], v[134:137], v[16:31]
	v_mfma_f32_32x32x16_bf16 v[0:15], v[172:175], v[134:137], v[0:15]
	ds_read_b128 v[130:133], v155 offset:49152
	ds_read_b128 v[134:137], v155 offset:53248
	ds_read_b128 v[150:153], v170
	ds_read_b128 v[172:175], v170 offset:4096
	s_waitcnt lgkmcnt(0)
	v_mfma_f32_32x32x16_bf16 v[48:63], v[150:153], v[130:133], v[48:63]
	v_mfma_f32_32x32x16_bf16 v[32:47], v[172:175], v[130:133], v[32:47]
	v_lshl_add_u64 v[130:131], v[146:147], 0, s[66:67]
	v_mfma_f32_32x32x16_bf16 v[16:31], v[184:187], v[180:183], v[16:31]
	v_mfma_f32_32x32x16_bf16 v[0:15], v[188:191], v[180:183], v[0:15]
	ds_read_b128 v[176:179], v156 offset:49152
	ds_read_b128 v[154:157], v156 offset:53248
	ds_read_b128 v[180:183], v171
	ds_read_b128 v[168:171], v171 offset:4096
	v_mov_b64_e32 v[132:133], v[208:209]
	s_waitcnt lgkmcnt(0)
;     DEVINL bf16_t* Z() const { return (bf16_t*)(ws + OFF_Z); }
; DEVINL float bflo(unsigned u) { return __uint_as_float(u << 16); }
; DEVINL float bfhi(unsigned u) { return __uint_as_float(u & 0xffff0000u); }
; DEVINL float* mp_row(const Ctx& c, int t) { return (float*)(c.Z() + (size_t)t * ZW); }
; template <int NI, int MODE>
; DEVINL void merge_tile(const Ctx& c, unsigned char* lds, int m0, int n0) {
;     ...
;         for (int mi = 0; mi < 2; ++mi) {
;             const bf16_t* gp = c.Z() + (size_t)(mbase + mi * 32 + r) * ZW + Z_GZ + br * DM + nbase;
; #pragma unroll
;             for (int ni = 0; ni < NI; ++ni)
; #pragma unroll
;                 for (int g = 0; g < 4; ++g) {
;                     const u32x2 gg = *(const u32x2*)(gp + ni * 32 + 8 * g + 4 * h);
;                     mer[ni][mi][4 * g + 0] += bflo(gg[0]) * acc[ni][mi][4 * g + 0];
;                     mer[ni][mi][4 * g + 1] += bfhi(gg[0]) * acc[ni][mi][4 * g + 1];
;                     mer[ni][mi][4 * g + 2] += bflo(gg[1]) * acc[ni][mi][4 * g + 2];
;                     mer[ni][mi][4 * g + 3] += bfhi(gg[1]) * acc[ni][mi][4 * g + 3];
;                 }
;         }
;     }
;     if (MODE == 0) {
; #pragma unroll
;         for (int mi = 0; mi < 2; ++mi) {
;             float* pp = mp_row(c, mbase + mi * 32 + r) + nbase;
; #pragma unroll
;             for (int ni = 0; ni < NI; ++ni)
; #pragma unroll
;                 for (int g = 0; g < 4; ++g) {
;                     f32x4 v = {mer[ni][mi][4 * g], mer[ni][mi][4 * g + 1], mer[ni][mi][4 * g + 2], mer[ni][mi][4 * g + 3]};
;                     *(f32x4*)(pp + ni * 32 + 8 * g + 4 * h) = v;
;                 }
;         }
	v_mfma_f32_32x32x16_bf16 v[48:63], v[180:183], v[176:179], v[48:63]
	v_mfma_f32_32x32x16_bf16 v[16:31], v[150:153], v[134:137], v[16:31]
	v_mfma_f32_32x32x16_bf16 v[0:15], v[172:175], v[134:137], v[0:15]
	s_nop 0
	v_lshlrev_b32_e32 v134, 16, v132
	v_and_b32_e32 v135, 0xffff0000, v132
	s_nop 6
	v_fma_f32 v126, v48, v134, v126
	v_fma_f32 v127, v49, v135, v127
	v_lshlrev_b32_e32 v48, 16, v133
	v_and_b32_e32 v49, 0xffff0000, v133
	v_pk_fma_f32 v[128:129], v[50:51], v[48:49], v[128:129]
	v_mov_b64_e32 v[48:49], v[210:211]
	v_mfma_f32_32x32x16_bf16 v[32:47], v[168:171], v[176:179], v[32:47]
	s_nop 0
	v_lshlrev_b32_e32 v50, 16, v48
	v_and_b32_e32 v51, 0xffff0000, v48
	v_lshlrev_b32_e32 v48, 16, v49
	v_and_b32_e32 v49, 0xffff0000, v49
	v_pk_fma_f32 v[124:125], v[54:55], v[48:49], v[124:125]
	v_mov_b64_e32 v[48:49], v[212:213]
	v_pk_fma_f32 v[122:123], v[52:53], v[50:51], v[122:123]
	v_mfma_f32_32x32x16_bf16 v[16:31], v[180:183], v[154:157], v[16:31]
	s_nop 0
	v_lshlrev_b32_e32 v50, 16, v48
	v_and_b32_e32 v51, 0xffff0000, v48
	v_lshlrev_b32_e32 v48, 16, v49
	v_and_b32_e32 v49, 0xffff0000, v49
	v_pk_fma_f32 v[120:121], v[58:59], v[48:49], v[120:121]
	v_mov_b64_e32 v[48:49], v[214:215]
	v_pk_fma_f32 v[118:119], v[56:57], v[50:51], v[118:119]
	v_mfma_f32_32x32x16_bf16 v[0:15], v[168:171], v[154:157], v[0:15]
	s_nop 0
	v_lshlrev_b32_e32 v50, 16, v48
	v_and_b32_e32 v51, 0xffff0000, v48
	v_lshlrev_b32_e32 v48, 16, v49
	v_and_b32_e32 v49, 0xffff0000, v49
	v_pk_fma_f32 v[116:117], v[62:63], v[48:49], v[116:117]
	v_mov_b64_e32 v[48:49], v[216:217]
	v_pk_fma_f32 v[114:115], v[60:61], v[50:51], v[114:115]
	s_nop 0
	v_lshlrev_b32_e32 v50, 16, v48
	v_and_b32_e32 v51, 0xffff0000, v48
	v_pk_fma_f32 v[110:111], v[32:33], v[50:51], v[110:111]
	v_lshlrev_b32_e32 v32, 16, v49
	v_and_b32_e32 v33, 0xffff0000, v49
	v_pk_fma_f32 v[112:113], v[34:35], v[32:33], v[112:113]
	v_mov_b64_e32 v[32:33], v[218:219]
	s_nop 0
	v_lshlrev_b32_e32 v34, 16, v32
	v_and_b32_e32 v35, 0xffff0000, v32
	v_lshlrev_b32_e32 v32, 16, v33
	v_and_b32_e32 v33, 0xffff0000, v33
	v_pk_fma_f32 v[108:109], v[38:39], v[32:33], v[108:109]
	v_mov_b64_e32 v[32:33], v[228:229]
	v_pk_fma_f32 v[106:107], v[36:37], v[34:35], v[106:107]
	s_nop 0
	v_lshlrev_b32_e32 v34, 16, v32
	v_and_b32_e32 v35, 0xffff0000, v32
	v_lshlrev_b32_e32 v32, 16, v33
	v_and_b32_e32 v33, 0xffff0000, v33
	v_pk_fma_f32 v[104:105], v[42:43], v[32:33], v[104:105]
	v_mov_b64_e32 v[32:33], v[254:255]
	v_pk_fma_f32 v[102:103], v[40:41], v[34:35], v[102:103]
	s_nop 0
	v_lshlrev_b32_e32 v34, 16, v32
	v_and_b32_e32 v35, 0xffff0000, v32
	v_lshlrev_b32_e32 v32, 16, v33
	v_and_b32_e32 v33, 0xffff0000, v33
	v_pk_fma_f32 v[88:89], v[46:47], v[32:33], v[88:89]
	v_lshl_add_u64 v[32:33], v[148:149], 0, s[66:67]
	v_pk_fma_f32 v[86:87], v[44:45], v[34:35], v[86:87]
	v_mov_b64_e32 v[34:35], v[230:231]
	s_nop 0
	v_lshlrev_b32_e32 v36, 16, v34
	v_and_b32_e32 v37, 0xffff0000, v34
	v_pk_fma_f32 v[98:99], v[16:17], v[36:37], v[98:99]
	v_lshlrev_b32_e32 v16, 16, v35
	v_and_b32_e32 v17, 0xffff0000, v35
	v_pk_fma_f32 v[100:101], v[18:19], v[16:17], v[100:101]
	v_mov_b64_e32 v[16:17], v[232:233]
	s_nop 0
	v_lshlrev_b32_e32 v18, 16, v16
	v_and_b32_e32 v19, 0xffff0000, v16
	v_lshlrev_b32_e32 v16, 16, v17
	v_and_b32_e32 v17, 0xffff0000, v17
	v_pk_fma_f32 v[96:97], v[22:23], v[16:17], v[96:97]
	v_mov_b64_e32 v[16:17], v[234:235]
	v_pk_fma_f32 v[94:95], v[20:21], v[18:19], v[94:95]
	s_nop 0
	v_lshlrev_b32_e32 v18, 16, v16
	v_and_b32_e32 v19, 0xffff0000, v16
	v_lshlrev_b32_e32 v16, 16, v17
	v_and_b32_e32 v17, 0xffff0000, v17
	v_pk_fma_f32 v[92:93], v[26:27], v[16:17], v[92:93]
	v_mov_b64_e32 v[16:17], v[236:237]
	v_pk_fma_f32 v[90:91], v[24:25], v[18:19], v[90:91]
	s_nop 0
	v_lshlrev_b32_e32 v18, 16, v16
	v_and_b32_e32 v19, 0xffff0000, v16
	v_lshlrev_b32_e32 v16, 16, v17
	v_and_b32_e32 v17, 0xffff0000, v17
	v_pk_fma_f32 v[84:85], v[30:31], v[16:17], v[84:85]
	v_mov_b64_e32 v[16:17], v[248:249]
	v_pk_fma_f32 v[82:83], v[28:29], v[18:19], v[82:83]
	s_nop 0
	v_lshlrev_b32_e32 v18, 16, v16
	v_and_b32_e32 v19, 0xffff0000, v16
	v_pk_fma_f32 v[78:79], v[0:1], v[18:19], v[78:79]
	v_lshlrev_b32_e32 v0, 16, v17
	v_and_b32_e32 v1, 0xffff0000, v17
	v_pk_fma_f32 v[80:81], v[2:3], v[0:1], v[80:81]
	v_mov_b64_e32 v[0:1], v[250:251]
	s_nop 0
	v_lshlrev_b32_e32 v2, 16, v0
	v_and_b32_e32 v3, 0xffff0000, v0
	v_lshlrev_b32_e32 v0, 16, v1
	v_and_b32_e32 v1, 0xffff0000, v1
	v_pk_fma_f32 v[76:77], v[6:7], v[0:1], v[76:77]
	v_mov_b64_e32 v[0:1], v[252:253]
	v_pk_fma_f32 v[74:75], v[4:5], v[2:3], v[74:75]
	s_nop 0
	v_lshlrev_b32_e32 v2, 16, v0
	v_and_b32_e32 v3, 0xffff0000, v0
	v_lshlrev_b32_e32 v0, 16, v1
	v_and_b32_e32 v1, 0xffff0000, v1
	v_pk_fma_f32 v[72:73], v[10:11], v[0:1], v[72:73]
	v_mov_b64_e32 v[0:1], v[242:243]
	v_pk_fma_f32 v[70:71], v[8:9], v[2:3], v[70:71]
	s_nop 0
	v_lshlrev_b32_e32 v2, 16, v0
	v_and_b32_e32 v3, 0xffff0000, v0
	v_lshlrev_b32_e32 v0, 16, v1
	v_and_b32_e32 v1, 0xffff0000, v1
	v_pk_fma_f32 v[66:67], v[12:13], v[2:3], v[66:67]
	v_pk_fma_f32 v[68:69], v[14:15], v[0:1], v[68:69]
	s_cbranch_scc1 .LBB0_290
	v_readlane_b32 s4, v247, 7
	v_readlane_b32 s5, v247, 8
	v_lshlrev_b64 v[2:3], 2, v[140:141]
	v_lshlrev_b32_e32 v64, 2, v142
	v_lshl_add_u64 v[0:1], s[4:5], 0, v[144:145]
	v_lshl_add_u64 v[0:1], v[0:1], 0, v[2:3]
	v_lshl_add_u64 v[0:1], v[0:1], 0, v[64:65]
	global_store_dwordx4 v[0:1], v[126:129], off
	global_store_dwordx4 v[0:1], v[122:125], off offset:32
	global_store_dwordx4 v[0:1], v[118:121], off offset:64
	global_store_dwordx4 v[0:1], v[114:117], off offset:96
	global_store_dwordx4 v[0:1], v[110:113], off offset:128
	global_store_dwordx4 v[0:1], v[106:109], off offset:160
	global_store_dwordx4 v[0:1], v[102:105], off offset:192
	global_store_dwordx4 v[0:1], v[86:89], off offset:224
	v_lshl_add_u64 v[0:1], s[4:5], 0, v[138:139]
	v_readlane_b32 s4, v247, 58
	s_add_i32 s1, s1, s4
	s_and_b32 s4, s1, -8
	v_lshl_add_u64 v[0:1], v[0:1], 0, v[2:3]
	s_or_b32 s4, s4, s0
	v_lshl_add_u64 v[0:1], v[0:1], 0, v[64:65]
	s_cmpk_gt_i32 s4, 0x43
	s_movk_i32 s49, 0x4400
	global_store_dwordx4 v[0:1], v[98:101], off
	global_store_dwordx4 v[0:1], v[94:97], off offset:32
	global_store_dwordx4 v[0:1], v[90:93], off offset:64
	global_store_dwordx4 v[0:1], v[82:85], off offset:96
	global_store_dwordx4 v[0:1], v[78:81], off offset:128
	global_store_dwordx4 v[0:1], v[74:77], off offset:160
	global_store_dwordx4 v[0:1], v[70:73], off offset:192
	global_store_dwordx4 v[0:1], v[66:69], off offset:224
	s_cbranch_scc0 .LBB0_289

; __global__ void __launch_bounds__(NTHR) fwd_megakernel(Params P) {
	.amdhsa_kernel _Z14fwd_megakernel6Params
		.amdhsa_group_segment_fixed_size 0
		.amdhsa_private_segment_fixed_size 0
		.amdhsa_kernarg_size 512
		.amdhsa_user_sgpr_count 2
		.amdhsa_user_sgpr_dispatch_ptr 0
		.amdhsa_user_sgpr_queue_ptr 0
		.amdhsa_user_sgpr_kernarg_segment_ptr 1
		.amdhsa_user_sgpr_dispatch_id 0
		.amdhsa_user_sgpr_kernarg_preload_length 0
		.amdhsa_user_sgpr_kernarg_preload_offset 0
		.amdhsa_user_sgpr_private_segment_size 0
		.amdhsa_uses_dynamic_stack 0
		.amdhsa_enable_private_segment 0
		.amdhsa_system_sgpr_workgroup_id_x 1
		.amdhsa_system_sgpr_workgroup_id_y 0
		.amdhsa_system_sgpr_workgroup_id_z 0
		.amdhsa_system_sgpr_workgroup_info 0
		.amdhsa_system_vgpr_workitem_id 2
		.amdhsa_next_free_vgpr 256
		.amdhsa_next_free_sgpr 102
		.amdhsa_accum_offset 256
		.amdhsa_reserve_vcc 1
		.amdhsa_float_round_mode_32 0
		.amdhsa_float_round_mode_16_64 0
		.amdhsa_float_denorm_mode_32 3
		.amdhsa_float_denorm_mode_16_64 3
		.amdhsa_dx10_clamp 1
		.amdhsa_ieee_mode 1
		.amdhsa_fp16_overflow 0
		.amdhsa_tg_split 0
		.amdhsa_exception_fp_ieee_invalid_op 0
		.amdhsa_exception_fp_denorm_src 0
		.amdhsa_exception_fp_ieee_div_zero 0
		.amdhsa_exception_fp_ieee_overflow 0
		.amdhsa_exception_fp_ieee_underflow 0
		.amdhsa_exception_fp_ieee_inexact 0
		.amdhsa_exception_int_div_zero 0
	.end_amdhsa_kernel

; __global__ void __launch_bounds__(NTHR) fwd_megakernel(Params P) {
amdhsa.kernels:
  - .agpr_count:     0
    .args:
      - .offset:         0
        .size:           256
        .value_kind:     by_value
      - .offset:         256
        .size:           4
        .value_kind:     hidden_block_count_x
      - .offset:         260
        .size:           4
        .value_kind:     hidden_block_count_y
      - .offset:         264
        .size:           4
        .value_kind:     hidden_block_count_z
      - .offset:         268
        .size:           2
        .value_kind:     hidden_group_size_x
      - .offset:         270
        .size:           2
        .value_kind:     hidden_group_size_y
      - .offset:         272
        .size:           2
        .value_kind:     hidden_group_size_z
      - .offset:         274
        .size:           2
        .value_kind:     hidden_remainder_x
      - .offset:         276
        .size:           2
        .value_kind:     hidden_remainder_y
      - .offset:         278
        .size:           2
        .value_kind:     hidden_remainder_z
      - .offset:         296
        .size:           8
        .value_kind:     hidden_global_offset_x
      - .offset:         304
        .size:           8
        .value_kind:     hidden_global_offset_y
      - .offset:         312
        .size:           8
        .value_kind:     hidden_global_offset_z
      - .offset:         320
        .size:           2
        .value_kind:     hidden_grid_dims
      - .offset:         344
        .size:           8
        .value_kind:     hidden_multigrid_sync_arg
      - .offset:         376
        .size:           4
        .value_kind:     hidden_dynamic_lds_size
    .group_segment_fixed_size: 0
    .kernarg_segment_align: 8
    .kernarg_segment_size: 512
    .language:       OpenCL C
    .language_version:
      - 2
      - 0
    .max_flat_workgroup_size: 512
    .name:           _Z14fwd_megakernel6Params
    .private_segment_fixed_size: 0
    .sgpr_count:     108
    .sgpr_spill_count: 171
    .symbol:         _Z14fwd_megakernel6Params.kd
    .uniform_work_group_size: 1
    .uses_dynamic_stack: false
    .vgpr_count:     256
    .vgpr_spill_count: 0
    .wavefront_size: 64
